# attn M phase runs at s_setprio 3 instead of 2
# baseline (speedup 1.0000x reference)
; #define SBAR() __builtin_amdgcn_sched_barrier(0)
; __device__ __forceinline__ void pv_d0(f32x16* o, int vb, bf16x8 pa0, bf16x8 pa1, bf16x8 pa2, bf16x8 pa3) {
;   const s16x4 a0 = tr_read<v_rd_off(0, 0, 0)>(vb), b0 = tr_read<v_rd_off(0, 0, 1)>(vb), a1 = tr_read<v_rd_off(0, 1, 0)>(vb), b1 = tr_read<v_rd_off(0, 1, 1)>(vb);
;   const s16x4 a2 = tr_read<v_rd_off(0, 2, 0)>(vb), b2 = tr_read<v_rd_off(0, 2, 1)>(vb), a3 = tr_read<v_rd_off(0, 3, 0)>(vb), b3 = tr_read<v_rd_off(0, 3, 1)>(vb);
;   const s16x4 c0 = tr_read<v_rd_off(1, 0, 0)>(vb), d0 = tr_read<v_rd_off(1, 0, 1)>(vb), c1 = tr_read<v_rd_off(1, 1, 0)>(vb), d1 = tr_read<v_rd_off(1, 1, 1)>(vb);
;   const s16x4 c2 = tr_read<v_rd_off(1, 2, 0)>(vb), d2 = tr_read<v_rd_off(1, 2, 1)>(vb), c3 = tr_read<v_rd_off(1, 3, 0)>(vb), d3 = tr_read<v_rd_off(1, 3, 1)>(vb);
;   asm volatile("s_waitcnt lgkmcnt(0)" ::: "memory"); SBAR();
.LBB0_524:
	s_mov_b32 s22, s0
	s_setprio 3
	v_add_u32_e32 v174, s22, v156
	ds_read_b64_tr_b16 v[66:67], v174 offset:0
	ds_read_b64_tr_b16 v[68:69], v174 offset:0x800
	ds_read_b64_tr_b16 v[158:159], v174 offset:0x200
	ds_read_b64_tr_b16 v[160:161], v174 offset:0xa00

; __device__ __forceinline__ void softmaxT(f32x16& p0, f32x16& p1, float& mref, f32x16& negm, float& l_reg, float& alpha, bf16x8& pa0, bf16x8& pa1, bf16x8& pa2, bf16x8& pa3) {
;     ...
;   { float s0 = p0[0] + p1[0], s1 = p0[1] + p1[1], s2 = p0[2] + p1[2], s3 = p0[3] + p1[3];
; #pragma unroll
;     for (int r = 4; r < 16; r += 4) { s0 += p0[r] + p1[r]; s1 += p0[r + 1] + p1[r + 1]; s2 += p0[r + 2] + p1[r + 2]; s3 += p0[r + 3] + p1[r + 3]; }
;     l_reg += (s0 + s1) + (s2 + s3); }
; __device__ __forceinline__ void qkt(f32x16& p0, f32x16& p1, const LAS unsigned char* Ks, const bf16x8* qr, const f32x16& negm, int r32, int hi) {
;   bf16x8 kf[12];
; #pragma unroll
;   for (int d0 = 0; d0 < 6; ++d0) { const int cb = (d0 * 16 + hi * 8) * 2;
;     kf[2 * d0] = *(const LAS bf16x8*)(Ks + KSWZ(r32, cb)); kf[2 * d0 + 1] = *(const LAS bf16x8*)(Ks + KSWZ(32 + r32, cb)); }
;   SBAR();
;   p0 = __builtin_amdgcn_mfma_f32_32x32x16_bf16(kf[0], qr[0], negm, 0, 0, 0); p1 = __builtin_amdgcn_mfma_f32_32x32x16_bf16(kf[1], qr[0], negm, 0, 0, 0);
; #pragma unroll
;   for (int d0 = 1; d0 < 6; ++d0) { p0 = __builtin_amdgcn_mfma_f32_32x32x16_bf16(kf[2 * d0], qr[d0], p0, 0, 0, 0); p1 = __builtin_amdgcn_mfma_f32_32x32x16_bf16(kf[2 * d0 + 1], qr[d0], p1, 0, 0, 0); }
; }
; __device__ __forceinline__ int v_st(int k, int c) { const int kk = (k & ~0xC) | ((k & 4) << 1) | ((k & 8) >> 1); return ((kk >> 3) * 4 + (c >> 5)) * 512 + ((kk & 7) * 32 + (c & 31)) * 2; }
; __device__ __forceinline__ int v_rd_base(int lane) { return ((lane & 3) << 3) | (((lane >> 2) & 3) << 6) | (((lane >> 4) & 1) << 5) | (((lane >> 5) & 1) << 8); }
; template <int OFF> __device__ __forceinline__ s16x4 tr_read(int vb) {
;   s16x4 r; asm volatile("ds_read_b64_tr_b16 %0, %1 offset:%2" : "=&v"(r) : "v"(vb), "i"(OFF) : "memory"); return r;
; }
; __device__ __forceinline__ void pv_d0(f32x16* o, int vb, bf16x8 pa0, bf16x8 pa1, bf16x8 pa2, bf16x8 pa3) {
;   const s16x4 a0 = tr_read<v_rd_off(0, 0, 0)>(vb), b0 = tr_read<v_rd_off(0, 0, 1)>(vb), a1 = tr_read<v_rd_off(0, 1, 0)>(vb), b1 = tr_read<v_rd_off(0, 1, 1)>(vb);
;   const s16x4 a2 = tr_read<v_rd_off(0, 2, 0)>(vb), b2 = tr_read<v_rd_off(0, 2, 1)>(vb), a3 = tr_read<v_rd_off(0, 3, 0)>(vb), b3 = tr_read<v_rd_off(0, 3, 1)>(vb);
;   const s16x4 c0 = tr_read<v_rd_off(1, 0, 0)>(vb), d0 = tr_read<v_rd_off(1, 0, 1)>(vb), c1 = tr_read<v_rd_off(1, 1, 0)>(vb), d1 = tr_read<v_rd_off(1, 1, 1)>(vb);
.LBB0_531:
	v_pk_add_f32 v[222:223], v[66:67], v[222:223]
	v_pk_add_f32 v[224:225], v[68:69], v[224:225]
	v_pk_add_f32 v[226:227], v[70:71], v[226:227]
	v_pk_add_f32 v[228:229], v[72:73], v[228:229]
	v_pk_add_f32 v[230:231], v[74:75], v[230:231]
	v_pk_add_f32 v[232:233], v[76:77], v[232:233]
	v_pk_add_f32 v[234:235], v[78:79], v[234:235]
	v_pk_add_f32 v[236:237], v[80:81], v[236:237]
	v_pk_add_f32 v[222:223], v[222:223], v[224:225]
	v_pk_add_f32 v[226:227], v[226:227], v[228:229]
	v_pk_add_f32 v[230:231], v[230:231], v[232:233]
	v_pk_add_f32 v[234:235], v[234:235], v[236:237]
	v_pk_add_f32 v[222:223], v[222:223], v[226:227]
	v_pk_add_f32 v[230:231], v[230:231], v[234:235]
	v_pk_add_f32 v[222:223], v[222:223], v[230:231]
	v_add_f32_e32 v222, v222, v223
	v_add_f32_e32 v157, v157, v222
	v_add_u32_e32 v174, s5, v156
	ds_read_b64_tr_b16 v[66:67], v174 offset:0
	ds_read_b64_tr_b16 v[68:69], v174 offset:0x800
	ds_read_b64_tr_b16 v[158:159], v174 offset:0x200
	ds_read_b64_tr_b16 v[160:161], v174 offset:0xa00
	s_waitcnt lgkmcnt(4)
	s_barrier
	s_setprio 3
	ds_read_b64_tr_b16 v[70:71], v174 offset:0x1000
	ds_read_b64_tr_b16 v[72:73], v174 offset:0x1800
	ds_read_b64_tr_b16 v[162:163], v174 offset:0x1200
	ds_read_b64_tr_b16 v[164:165], v174 offset:0x1a00
	ds_read_b64_tr_b16 v[74:75], v174 offset:0x2000
	ds_read_b64_tr_b16 v[76:77], v174 offset:0x2800
	ds_read_b64_tr_b16 v[166:167], v174 offset:0x2200
	ds_read_b64_tr_b16 v[168:169], v174 offset:0x2a00
	ds_read_b64_tr_b16 v[78:79], v174 offset:0x3000
	ds_read_b64_tr_b16 v[80:81], v174 offset:0x3800
	ds_read_b64_tr_b16 v[170:171], v174 offset:0x3200
	ds_read_b64_tr_b16 v[172:173], v174 offset:0x3a00
	s_waitcnt lgkmcnt(14)
	v_mfma_f32_32x32x16_bf16 v[34:49], v[54:57], v[66:69], v[34:49]
	s_waitcnt lgkmcnt(12)
	v_mfma_f32_32x32x16_bf16 v[18:33], v[54:57], v[158:161], v[18:33]
	v_add_u32_e32 v54, s10, v146
	v_add_u32_e32 v55, v54, v147
	s_waitcnt lgkmcnt(10)
	v_mfma_f32_32x32x16_bf16 v[34:49], v[50:53], v[70:73], v[34:49]
	s_waitcnt lgkmcnt(8)
	v_mfma_f32_32x32x16_bf16 v[18:33], v[50:53], v[162:165], v[18:33]
	ds_read_b128 v[50:53], v55 offset:49152
	ds_read_b128 v[158:161], v55 offset:57344
	v_add_u32_e32 v55, v54, v148
	s_waitcnt lgkmcnt(8)
	v_mfma_f32_32x32x16_bf16 v[34:49], v[58:61], v[74:77], v[34:49]
	s_waitcnt lgkmcnt(6)
	v_mfma_f32_32x32x16_bf16 v[18:33], v[58:61], v[166:169], v[18:33]
	ds_read_b128 v[162:165], v55 offset:49152
	ds_read_b128 v[166:169], v55 offset:57344
	v_add_u32_e32 v55, v54, v149
	s_waitcnt lgkmcnt(6)
	v_mfma_f32_32x32x16_bf16 v[34:49], v[62:65], v[78:81], v[34:49]
	s_waitcnt lgkmcnt(4)
	v_mfma_f32_32x32x16_bf16 v[18:33], v[62:65], v[170:173], v[18:33]
	ds_read_b128 v[170:173], v55 offset:49152
	ds_read_b128 v[178:181], v55 offset:57344
	v_add_u32_e32 v55, v54, v150
	ds_read_b128 v[182:185], v55 offset:49152
	ds_read_b128 v[186:189], v55 offset:57344
	v_add_u32_e32 v55, v54, v151
	v_add_u32_e32 v54, v54, v152
	ds_read_b128 v[190:193], v55 offset:49152
	ds_read_b128 v[194:197], v55 offset:57344
	ds_read_b128 v[198:201], v54 offset:49152
	ds_read_b128 v[202:205], v54 offset:57344
	s_waitcnt lgkmcnt(11)
	v_mfma_f32_32x32x16_bf16 v[66:81], v[50:53], v[82:85], v[2:17]
	s_waitcnt lgkmcnt(9)
	v_mfma_f32_32x32x16_bf16 v[66:81], v[162:165], v[86:89], v[66:81]
	s_waitcnt lgkmcnt(7)
	v_mfma_f32_32x32x16_bf16 v[66:81], v[170:173], v[90:93], v[66:81]
	s_waitcnt lgkmcnt(5)
	v_mfma_f32_32x32x16_bf16 v[66:81], v[182:185], v[94:97], v[66:81]
	s_waitcnt lgkmcnt(3)
	v_mfma_f32_32x32x16_bf16 v[66:81], v[190:193], v[98:101], v[66:81]
	s_waitcnt lgkmcnt(1)
	v_mfma_f32_32x32x16_bf16 v[66:81], v[198:201], v[102:105], v[66:81]
	s_waitcnt lgkmcnt(0)
	v_mfma_f32_32x32x16_bf16 v[50:65], v[158:161], v[82:85], v[2:17]
	v_mfma_f32_32x32x16_bf16 v[50:65], v[166:169], v[86:89], v[50:65]
	v_mfma_f32_32x32x16_bf16 v[50:65], v[178:181], v[90:93], v[50:65]
	v_mfma_f32_32x32x16_bf16 v[50:65], v[186:189], v[94:97], v[50:65]
	v_mfma_f32_32x32x16_bf16 v[50:65], v[194:197], v[98:101], v[50:65]
	v_mfma_f32_32x32x16_bf16 v[50:65], v[202:205], v[102:105], v[50:65]
	s_setprio 0
	v_max3_f32 v158, v66, v67, v68
	v_max3_f32 v159, v69, v70, v71
	v_max3_f32 v158, v158, v72, v73
	v_max3_f32 v159, v159, v74, v75
	v_max3_f32 v158, v158, v76, v77
	v_max3_f32 v159, v159, v78, v79
	v_max3_f32 v158, v158, v80, v81
	s_nop 3
	v_max3_f32 v159, v159, v50, v51
	v_max3_f32 v158, v158, v52, v53
	v_max3_f32 v159, v159, v54, v55
	v_max3_f32 v158, v158, v56, v57
	v_max3_f32 v159, v159, v58, v59
	v_max3_f32 v158, v158, v60, v61
	v_max3_f32 v159, v159, v62, v63
	v_max3_f32 v158, v158, v64, v65
	v_max_f32_e32 v159, v158, v159
	v_cmp_ge_f32_e32 vcc, s93, v159
	s_cmp_eq_u64 vcc, exec
	v_mov_b32_e32 v158, 1.0
	s_barrier
	s_cbranch_scc0 .LBB0_541

; #define PHASE_M(j) do { SBAR(); __builtin_amdgcn_s_setprio(2); if ((j) > 0) pv_d0(o, vb0 + bV, pa0, pa1, pa2, pa3); qkt(p0, p1, Kb + bK, qr, negm, r32, hi); __builtin_amdgcn_s_setprio(0); SBAR(); __syncthreads(); } while (0)
; #define PHASE_V(j, slot) do { softmaxT(p0, p1, mref, negm, l_reg, alpha, pa0, pa1, pa2, pa3); RESC(alpha); \
;     { const int s_ = (j) + 1 + trail; if (s_ < NT) { asm volatile("s_waitcnt vmcnt(3)" ::: "memory"); SWRITE_AT(trail ? bNN : bN, slot); const int s2_ = s_ + 2; SLOAD(slot, s2_ < NT ? s2_ : NT - 1); } } \
;     __syncthreads(); bV = bK; bK = bN; bN = bNN; bNN = bV; } while (0)
; __device__ __forceinline__ void softmaxT(f32x16& p0, f32x16& p1, float& mref, f32x16& negm, float& l_reg, float& alpha, bf16x8& pa0, bf16x8& pa1, bf16x8& pa2, bf16x8& pa3) {
;     ...
;   { float s0 = p0[0] + p1[0], s1 = p0[1] + p1[1], s2 = p0[2] + p1[2], s3 = p0[3] + p1[3];
; #pragma unroll
;     for (int r = 4; r < 16; r += 4) { s0 += p0[r] + p1[r]; s1 += p0[r + 1] + p1[r + 1]; s2 += p0[r + 2] + p1[r + 2]; s3 += p0[r + 3] + p1[r + 3]; }
;     l_reg += (s0 + s1) + (s2 + s3); }
; __device__ __forceinline__ void attn_unit(const bf16_t* __restrict__ Qb, bool rope_q, int tq0, const bf16_t* __restrict__ KVh, const bf16_t* __restrict__ KR,
;                                           int ctx_row0, int lat_row0, int NT, bf16_t* __restrict__ Ob, LAS unsigned char* lds, int wave_s) {
;     ...
;   for (int j = 0; j < NT; j += 2) {
;     PHASE_M(j); PHASE_V(j, 1);
;     PHASE_M(j + 1); PHASE_V(j + 1, 0);
;   }
.LBB0_538:
	v_pk_add_f32 v[222:223], v[66:67], v[222:223]
	v_pk_add_f32 v[224:225], v[68:69], v[224:225]
	v_pk_add_f32 v[226:227], v[70:71], v[226:227]
	v_pk_add_f32 v[228:229], v[72:73], v[228:229]
	v_pk_add_f32 v[230:231], v[74:75], v[230:231]
	v_pk_add_f32 v[232:233], v[76:77], v[232:233]
	v_pk_add_f32 v[234:235], v[78:79], v[234:235]
	v_pk_add_f32 v[236:237], v[80:81], v[236:237]
	v_pk_add_f32 v[222:223], v[222:223], v[224:225]
	v_pk_add_f32 v[226:227], v[226:227], v[228:229]
	v_pk_add_f32 v[230:231], v[230:231], v[232:233]
	v_pk_add_f32 v[234:235], v[234:235], v[236:237]
	v_pk_add_f32 v[222:223], v[222:223], v[226:227]
	v_pk_add_f32 v[230:231], v[230:231], v[234:235]
	v_pk_add_f32 v[222:223], v[222:223], v[230:231]
	v_add_f32_e32 v222, v222, v223
	s_add_i32 s11, s11, 2
	v_add_f32_e32 v157, v157, v222
	s_and_b64 vcc, exec, s[0:1]
	v_add_u32_e32 v174, s10, v156
	ds_read_b64_tr_b16 v[66:67], v174 offset:0
	ds_read_b64_tr_b16 v[68:69], v174 offset:0x800
	ds_read_b64_tr_b16 v[158:159], v174 offset:0x200
	ds_read_b64_tr_b16 v[160:161], v174 offset:0xa00
	s_waitcnt lgkmcnt(4)
	s_barrier
	s_cbranch_vccnz .LBB0_542
	s_mov_b32 s0, s10
	s_mov_b32 s10, s5
	s_mov_b32 s5, s22
	s_mov_b32 s22, s0
	s_setprio 3
	s_branch .Lmy_attn_m1
